# FFN2 weight copies moved into the lora phase (idle waves 5-7 of every WG); removed from the scan WGs in phase 6
# baseline (speedup 1.0000x reference)
; #define LAS __attribute__((address_space(3)))
; #define ws (p.ws())
; __device__ __forceinline__ void phase_lora(const Ctx& p, LAS unsigned char* lds) {
;     const int tid = threadIdx.x, lane = tid & 63, wave = __builtin_amdgcn_readfirstlane(tid >> 6), q = lane & 15, g = lane >> 4;
;     const bf16_t* ZRW = (const bf16_t*)(p.ws() + WS_ZRW);
;     float* DEC = (float*)(p.ws() + WS_DEC); bf16_t* AB = (bf16_t*)(p.ws() + WS_ABUF); bf16_t* GG = (bf16_t*)(p.ws() + WS_GG);
;     const bf16_t* w2T = (const bf16_t*)(p.ws() + WS_LW); const bf16_t* a2T = w2T + 512 * 64; const bf16_t* g2T = a2T + 512 * 64;
;     LAS bf16_t* X = (LAS bf16_t*)(lds + wave * 16 * 264 * 2);
;     const float* mu = p.in(17) + 1536;
;     for (int it = blockIdx.x + gridDim.x * wave; it < MR / 16; it += gridDim.x * 8) {
;         const int r0 = it * 16;
;         {
;             const int tt = lane >> 2, cq = lane & 3, row = r0 + tt;
; #pragma unroll
;             for (int j = 0; j < 8; ++j) {
;                 const int c = cq * 64 + j * 8;
;                 float m8[8], z[8];
; #pragma unroll
;                 for (int e = 0; e < 8; ++e) m8[e] = mu[c + e];
;                 zshift8(p, ZRW, row, 1536 + c, m8, z);
; #pragma unroll
;                 for (int e = 0; e < 8; ++e) z[e] = cq == 0 ? tanhf(z[e]) : (cq == 1 ? z[e] : sigmoidf_(z[e]));
;                 u32x4 w; w.x = pk2(z[0], z[1]); w.y = pk2(z[2], z[3]); w.z = pk2(z[4], z[5]); w.w = pk2(z[6], z[7]);
;                 *(LAS u32x4*)(X + tt * 264 + c) = w;
;             }
;         }
;         asm volatile("s_waitcnt lgkmcnt(0)" ::: "memory");
;         bf16x8 bx[8];
; #pragma unroll
;         for (int ks = 0; ks < 8; ++ks) bx[ks] = *(const LAS bf16x8*)(X + q * 264 + ks * 32 + 8 * g);
;         const int row = r0 + q;
;         struct WF { bf16x8 w[2], a[2], gq[4]; f32x4 w0, a0; };
;         auto ldw = [&](WF& f, int nt) {
;             const int n = nt * 16 + q, c = nt * 16 + 4 * g;
; #pragma unroll
;             for (int ks = 0; ks < 2; ++ks) { f.w[ks] = *(const bf16x8*)(w2T + n * 64 + ks * 32 + 8 * g); f.a[ks] = *(const bf16x8*)(a2T + n * 64 + ks * 32 + 8 * g); }
; #pragma unroll
;             for (int ks = 0; ks < 4; ++ks) f.gq[ks] = *(const bf16x8*)(g2T + n * 128 + ks * 32 + 8 * g);
;             f.w0 = *(const f32x4*)(p.in(18) + c); f.a0 = *(const f32x4*)(p.in(20) + c);
.LBB0_870:
	s_cmp_lt_i32 s36, 6
	s_cselect_b64 s[4:5], -1, 0
	s_and_b64 s[10:11], s[4:5], s[2:3]
	s_andn2_b64 vcc, exec, s[10:11]
	s_cbranch_vccnz .LBB0_1564
	s_waitcnt vmcnt(0)
	v_mov_b32_e32 v0, 0x23528
	v_mov_b32_e32 v1, 0x23488
	v_mov_b32_e32 v2, 0x23428
	v_mov_b32_e32 v3, 0x23490
	v_mov_b32_e32 v4, 0x234a0
	ds_read_b64 v[6:7], v0
	ds_read_b64 v[8:9], v1
	ds_read_b64 v[10:11], v2
	ds_read_b64 v[12:13], v3
	ds_read_b64 v[14:15], v4
	v_readfirstlane_b32 s2, v180
	s_waitcnt lgkmcnt(0)
	v_readfirstlane_b32 s12, v6
	v_readfirstlane_b32 s13, v7
	v_readfirstlane_b32 s16, v8
	v_readfirstlane_b32 s17, v9
	v_readfirstlane_b32 s18, v10
	v_readfirstlane_b32 s19, v11
	v_readfirstlane_b32 s20, v12
	v_readfirstlane_b32 s21, v13
	v_readfirstlane_b32 s22, v14
	v_readfirstlane_b32 s23, v15
	s_nop 4
	s_lshr_b32 s27, s2, 6
	s_mov_b32 s56, 0
	s_mul_i32 s2, s27, s38
	s_add_i32 s26, s2, s28
	s_add_u32 s14, s12, 0x8340000
	s_addc_u32 s15, s13, 0
	s_add_u32 s16, s16, 0x1800
	s_addc_u32 s17, s17, 0
	s_add_u32 s24, s12, 0x3110000
	s_addc_u32 s25, s13, 0
	s_add_u32 s40, s12, 0x3120000
	s_addc_u32 s41, s13, 0
	s_add_u32 s42, s12, 0x3130000
	s_addc_u32 s43, s13, 0
	s_add_u32 s44, s12, 0x3200000
	s_addc_u32 s45, s13, 0
	s_add_u32 s46, s12, 0x4240000
	s_addc_u32 s47, s13, 0
	s_add_u32 s54, s12, 0xfd20000
	s_addc_u32 s55, s13, 0
	v_and_b32_e32 v0, 63, v180
	v_lshrrev_b32_e32 v1, 2, v0
	v_and_b32_e32 v2, 3, v0
	v_and_b32_e32 v10, 15, v0
	v_lshrrev_b32_e32 v11, 4, v0
	v_cmp_eq_u32_e32 vcc, 0, v2
	v_mov_b32_e32 v12, 0xbfb8aa3b
	v_mov_b32_e32 v13, 0x4038aa3b
	v_cndmask_b32_e32 v7, v12, v13, vcc
	v_mov_b32_e32 v12, 1.0
	v_mov_b32_e32 v13, -2.0
	v_cndmask_b32_e32 v8, v12, v13, vcc
	v_mov_b32_e32 v12, 0
	v_mov_b32_e32 v13, 1.0
	v_cndmask_b32_e32 v9, v12, v13, vcc
	v_cmp_eq_u32_e64 s[48:49], 1, v2
	s_mul_i32 s3, s27, 0x2100
	v_mul_u32_u24_e32 v6, 0x210, v1
	v_lshl_add_u32 v6, v2, 7, v6
	v_add_u32_e32 v6, s3, v6
	v_mul_u32_u24_e32 v14, 0x210, v10
	v_lshl_add_u32 v14, v11, 4, v14
	v_add_u32_e32 v14, s3, v14
	v_lshlrev_b32_e32 v5, 8, v2
	s_lshr_b32 s2, s28, 3
	s_and_b32 s2, s2, 31
	s_lshl_b32 s2, s2, 13
	v_lshlrev_b32_e32 v12, 4, v180
	v_add_u32_e32 v12, s2, v12
	v_and_b32_e32 v13, 0x7f, v180
	v_lshlrev_b32_e32 v13, 4, v13
	global_load_dwordx4 v[164:167], v12, s[24:25]
	global_load_dwordx4 v[168:171], v13, s[20:21]
	global_load_dwordx4 v[172:175], v13, s[22:23]
	s_cmpk_gt_u32 s27, 4
	s_cbranch_scc1 .Llora_ffn2w

; #define LAS __attribute__((address_space(3)))
; __device__ __forceinline__ unsigned pk2(float lo, float hi) { f32x2 v = {lo, hi}; bf16x2_t b = __builtin_convertvector(v, bf16x2_t); return __builtin_bit_cast(unsigned, b); }
;     __device__ __forceinline__ const float* in(int i) const { return (const float*)ptr(i); }
;     __device__ __forceinline__ unsigned char* ws() const { return (unsigned char*)ptr(37); }
; #define ws (p.ws())
; __device__ __forceinline__ void transpose_item(const float* W, int K, int N, bf16_t* WT, int k0, int n0, int drow0, LAS float* scr, int lane) {
; #pragma unroll 8
;     for (int i = 0; i < 32; ++i) { const int kk = 2 * i + (lane >> 5); scr[kk * 33 + (lane & 31)] = W[(size_t)(k0 + kk) * N + n0 + (lane & 31)]; }
;     asm volatile("s_waitcnt lgkmcnt(0)" ::: "memory");
;     const int c = lane & 7;
; #pragma unroll
;     for (int j = 0; j < 4; ++j) { const int n = (lane >> 3) + 8 * j; const LAS float* s = scr + (8 * c) * 33 + n;
;         u32x4 o; o.x = pk2(s[0 * 33], s[1 * 33]); o.y = pk2(s[2 * 33], s[3 * 33]); o.z = pk2(s[4 * 33], s[5 * 33]); o.w = pk2(s[6 * 33], s[7 * 33]);
;         *(u32x4*)(WT + (size_t)(drow0 + n) * K + k0 + 8 * c) = o; }
;     asm volatile("s_waitcnt lgkmcnt(0)" ::: "memory");
; }
; __device__ __forceinline__ void ffn2_weights(const Ctx& p, LAS unsigned char* lds) {
;     const int tid = threadIdx.x, lane = tid & 63, wave = __builtin_amdgcn_readfirstlane(tid >> 6);
;     unsigned char* ws = p.ws();
;     LAS float* scr = (LAS float*)(lds + wave * 16384);
;     constexpr int I7 = 16 * 176, I8 = 44 * 32;
;     __syncthreads();
;     for (int it = ((int)blockIdx.x - 128) * 8 + wave; it < I7 + I8; it += 128 * 8) {
;         int r = it;
;         if (r < I7) { const int kb = r / 176, nb = r % 176; transpose_item(p.in(33), DM, NFF, (bf16_t*)(ws + WS_W3T), 64 * kb, 32 * nb, map_w1(32 * nb), scr, lane); continue; } r -= I7;
.Llora_ffn2w:
	v_mov_b32_e32 v0, 0x23508
	v_mov_b32_e32 v1, 0x23510
	v_mov_b32_e32 v2, 0x23528
	ds_read_b64 v[4:5], v0
	ds_read_b64 v[6:7], v1
	ds_read_b64 v[8:9], v2
	v_readfirstlane_b32 s2, v180
	s_waitcnt lgkmcnt(0)
	v_readfirstlane_b32 s8, v4
	v_readfirstlane_b32 s9, v5
	v_readfirstlane_b32 s58, v6
	v_readfirstlane_b32 s59, v7
	v_readfirstlane_b32 s12, v8
	v_readfirstlane_b32 s13, v9
	s_nop 4
	s_lshr_b32 s27, s2, 6
	s_mul_i32 s26, s28, 3
	s_add_i32 s26, s26, s27
	s_sub_u32 s26, s26, 5
	s_lshl_b32 s3, s27, 14
	v_and_b32_e32 v0, 63, v180
	v_lshrrev_b32_e32 v1, 3, v0
	v_and_b32_e32 v2, 7, v0
	v_mul_u32_u24_e32 v14, 0x84, v1
	v_lshl_add_u32 v14, v2, 4, v14
	v_add_u32_e32 v14, s3, v14
	v_mul_u32_u24_e32 v15, 0x420, v2
	v_lshl_add_u32 v15, v1, 2, v15
	v_add_u32_e32 v15, s3, v15
	v_mul_u32_u24_e32 v13, 0x5800, v1
	v_lshl_add_u32 v13, v2, 4, v13
	v_lshlrev_b32_e32 v4, 11, v1
	v_lshl_add_u32 v4, v2, 4, v4
	v_add_u32_e32 v5, 0x4000, v4
	v_add_u32_e32 v6, 0x8000, v4
	v_add_u32_e32 v7, 0xc000, v4
	s_add_u32 s18, s12, 0x1f00000
	s_addc_u32 s19, s13, 0
.Lffn2w_w3:
	s_cmpk_gt_u32 s26, 0xaff
	s_cbranch_scc1 .Lffn2w_w3_done
	s_mul_hi_u32 s4, s26, 0x1745d18
	s_mul_i32 s5, s4, 0xb0
	s_sub_u32 s5, s26, s5
	s_mul_i32 s6, s4, 0x160000
	s_lshl_b32 s7, s5, 7
	s_add_u32 s6, s6, s7
	s_add_u32 s14, s8, s6
	s_addc_u32 s15, s9, 0
	s_cmpk_lt_u32 s5, 0x58
	s_cselect_b32 s20, 0, 0x80
	s_cselect_b32 s21, 0, 0x58
	s_sub_u32 s5, s5, s21
	s_lshr_b32 s21, s5, 2
	s_lshl_b32 s21, s21, 8
	s_and_b32 s5, s5, 3
	s_lshl_b32 s5, s5, 5
	s_add_u32 s21, s21, s5
	s_add_u32 s21, s21, s20
	s_lshl_b32 s21, s21, 11
	s_lshl_b32 s4, s4, 7
	s_add_u32 s21, s21, s4
	s_add_u32 s16, s18, s21
	s_addc_u32 s17, s19, 0
	global_load_dwordx4 v[16:19], v13, s[14:15]
	v_add_u32_e32 v12, 0x2c000, v13
	global_load_dwordx4 v[20:23], v12, s[14:15]
	v_add_u32_e32 v12, 0x2c000, v12
	global_load_dwordx4 v[24:27], v12, s[14:15]
	v_add_u32_e32 v12, 0x2c000, v12
	global_load_dwordx4 v[28:31], v12, s[14:15]
	v_add_u32_e32 v12, 0x2c000, v12
	global_load_dwordx4 v[32:35], v12, s[14:15]
	v_add_u32_e32 v12, 0x2c000, v12
	global_load_dwordx4 v[36:39], v12, s[14:15]
	v_add_u32_e32 v12, 0x2c000, v12
	global_load_dwordx4 v[40:43], v12, s[14:15]
	v_add_u32_e32 v12, 0x2c000, v12
	global_load_dwordx4 v[44:47], v12, s[14:15]
	s_waitcnt vmcnt(7)
	ds_write_b32 v14, v16 offset:0
	ds_write_b32 v14, v17 offset:4
	ds_write_b32 v14, v18 offset:8
	ds_write_b32 v14, v19 offset:12
	s_waitcnt vmcnt(6)
	ds_write_b32 v14, v20 offset:1056
	ds_write_b32 v14, v21 offset:1060
	ds_write_b32 v14, v22 offset:1064
	ds_write_b32 v14, v23 offset:1068
	s_waitcnt vmcnt(5)
	ds_write_b32 v14, v24 offset:2112
	ds_write_b32 v14, v25 offset:2116
	ds_write_b32 v14, v26 offset:2120
	ds_write_b32 v14, v27 offset:2124
	s_waitcnt vmcnt(4)
	ds_write_b32 v14, v28 offset:3168
	ds_write_b32 v14, v29 offset:3172
	ds_write_b32 v14, v30 offset:3176
	ds_write_b32 v14, v31 offset:3180
	s_waitcnt vmcnt(3)
	ds_write_b32 v14, v32 offset:4224
	ds_write_b32 v14, v33 offset:4228
	ds_write_b32 v14, v34 offset:4232
	ds_write_b32 v14, v35 offset:4236
	s_waitcnt vmcnt(2)
	ds_write_b32 v14, v36 offset:5280
	ds_write_b32 v14, v37 offset:5284
	ds_write_b32 v14, v38 offset:5288
	ds_write_b32 v14, v39 offset:5292
	s_waitcnt vmcnt(1)
	ds_write_b32 v14, v40 offset:6336
	ds_write_b32 v14, v41 offset:6340
	ds_write_b32 v14, v42 offset:6344
	ds_write_b32 v14, v43 offset:6348
	s_waitcnt vmcnt(0)
	ds_write_b32 v14, v44 offset:7392
	ds_write_b32 v14, v45 offset:7396
	ds_write_b32 v14, v46 offset:7400
	ds_write_b32 v14, v47 offset:7404
	s_waitcnt lgkmcnt(0)
	ds_read2_b32 v[80:81], v15 offset0:0 offset1:33
	ds_read2_b32 v[82:83], v15 offset0:66 offset1:99
	ds_read2_b32 v[84:85], v15 offset0:132 offset1:165
	ds_read2_b32 v[86:87], v15 offset0:198 offset1:231
	ds_read2_b32 v[88:89], v15 offset0:8 offset1:41
	ds_read2_b32 v[90:91], v15 offset0:74 offset1:107
	ds_read2_b32 v[92:93], v15 offset0:140 offset1:173
	ds_read2_b32 v[94:95], v15 offset0:206 offset1:239
	s_waitcnt lgkmcnt(4)
	v_cvt_pk_bf16_f32 v112, v80, v81
	v_cvt_pk_bf16_f32 v113, v82, v83
	v_cvt_pk_bf16_f32 v114, v84, v85
	v_cvt_pk_bf16_f32 v115, v86, v87
	global_store_dwordx4 v4, v[112:115], s[16:17]
	s_waitcnt lgkmcnt(0)
	v_cvt_pk_bf16_f32 v116, v88, v89
	v_cvt_pk_bf16_f32 v117, v90, v91
	v_cvt_pk_bf16_f32 v118, v92, v93
	v_cvt_pk_bf16_f32 v119, v94, v95
	global_store_dwordx4 v5, v[116:119], s[16:17]
	ds_read2_b32 v[96:97], v15 offset0:16 offset1:49
	ds_read2_b32 v[98:99], v15 offset0:82 offset1:115
	ds_read2_b32 v[100:101], v15 offset0:148 offset1:181
	ds_read2_b32 v[102:103], v15 offset0:214 offset1:247
	ds_read2_b32 v[104:105], v15 offset0:24 offset1:57
	ds_read2_b32 v[106:107], v15 offset0:90 offset1:123
	ds_read2_b32 v[108:109], v15 offset0:156 offset1:189
	ds_read2_b32 v[110:111], v15 offset0:222 offset1:255
	s_waitcnt lgkmcnt(4)
	v_cvt_pk_bf16_f32 v120, v96, v97
	v_cvt_pk_bf16_f32 v121, v98, v99
	v_cvt_pk_bf16_f32 v122, v100, v101
	v_cvt_pk_bf16_f32 v123, v102, v103
	global_store_dwordx4 v6, v[120:123], s[16:17]
	s_waitcnt lgkmcnt(0)
	v_cvt_pk_bf16_f32 v124, v104, v105
	v_cvt_pk_bf16_f32 v125, v106, v107
	v_cvt_pk_bf16_f32 v126, v108, v109
	v_cvt_pk_bf16_f32 v127, v110, v111
	global_store_dwordx4 v7, v[124:127], s[16:17]
	s_addk_i32 s26, 0x300
	s_branch .Lffn2w_w3

; #define LAS __attribute__((address_space(3)))
; __device__ __forceinline__ unsigned pk2(float lo, float hi) { f32x2 v = {lo, hi}; bf16x2_t b = __builtin_convertvector(v, bf16x2_t); return __builtin_bit_cast(unsigned, b); }
;     __device__ __forceinline__ const float* in(int i) const { return (const float*)ptr(i); }
;     __device__ __forceinline__ unsigned char* ws() const { return (unsigned char*)ptr(37); }
; #define ws (p.ws())
; __device__ __forceinline__ void transpose_item(const float* W, int K, int N, bf16_t* WT, int k0, int n0, int drow0, LAS float* scr, int lane) {
; #pragma unroll 8
;     for (int i = 0; i < 32; ++i) { const int kk = 2 * i + (lane >> 5); scr[kk * 33 + (lane & 31)] = W[(size_t)(k0 + kk) * N + n0 + (lane & 31)]; }
;     asm volatile("s_waitcnt lgkmcnt(0)" ::: "memory");
;     const int c = lane & 7;
; #pragma unroll
;     for (int j = 0; j < 4; ++j) { const int n = (lane >> 3) + 8 * j; const LAS float* s = scr + (8 * c) * 33 + n;
;         u32x4 o; o.x = pk2(s[0 * 33], s[1 * 33]); o.y = pk2(s[2 * 33], s[3 * 33]); o.z = pk2(s[4 * 33], s[5 * 33]); o.w = pk2(s[6 * 33], s[7 * 33]);
;         *(u32x4*)(WT + (size_t)(drow0 + n) * K + k0 + 8 * c) = o; }
;     asm volatile("s_waitcnt lgkmcnt(0)" ::: "memory");
; }
; __device__ __forceinline__ void ffn2_weights(const Ctx& p, LAS unsigned char* lds) {
;     ...
;     for (int it = ((int)blockIdx.x - 128) * 8 + wave; it < I7 + I8; it += 128 * 8) {
;         int r = it;
;         if (r < I7) { const int kb = r / 176, nb = r % 176; transpose_item(p.in(33), DM, NFF, (bf16_t*)(ws + WS_W3T), 64 * kb, 32 * nb, map_w1(32 * nb), scr, lane); continue; } r -= I7;
;         { const int kb = r / 32, nb = r % 32; transpose_item(p.in(34), DFF, DM, (bf16_t*)(ws + WS_W4T), 64 * kb, 32 * nb, 32 * nb, scr, lane); }
;     }
.Lffn2w_w4:
	s_cmpk_gt_u32 s26, 0x57f
	s_cbranch_scc1 .Llora_done
	s_lshr_b32 s4, s26, 5
	s_and_b32 s5, s26, 31
	s_lshl_b32 s6, s4, 18
	s_lshl_b32 s7, s5, 7
	s_add_u32 s6, s6, s7
	s_add_u32 s14, s58, s6
	s_addc_u32 s15, s59, 0
	s_mul_i32 s21, s5, 0x2c000
	s_lshl_b32 s4, s4, 7
	s_add_u32 s21, s21, s4
	s_add_u32 s16, s18, s21
	s_addc_u32 s17, s19, 0
	global_load_dwordx4 v[16:19], v13, s[14:15]
	v_add_u32_e32 v12, 0x8000, v13
	global_load_dwordx4 v[20:23], v12, s[14:15]
	v_add_u32_e32 v12, 0x8000, v12
	global_load_dwordx4 v[24:27], v12, s[14:15]
	v_add_u32_e32 v12, 0x8000, v12
	global_load_dwordx4 v[28:31], v12, s[14:15]
	v_add_u32_e32 v12, 0x8000, v12
	global_load_dwordx4 v[32:35], v12, s[14:15]
	v_add_u32_e32 v12, 0x8000, v12
	global_load_dwordx4 v[36:39], v12, s[14:15]
	v_add_u32_e32 v12, 0x8000, v12
	global_load_dwordx4 v[40:43], v12, s[14:15]
	v_add_u32_e32 v12, 0x8000, v12
	global_load_dwordx4 v[44:47], v12, s[14:15]
	s_waitcnt vmcnt(7)
	ds_write_b32 v14, v16 offset:0
	ds_write_b32 v14, v17 offset:4
	ds_write_b32 v14, v18 offset:8
	ds_write_b32 v14, v19 offset:12
	s_waitcnt vmcnt(6)
	ds_write_b32 v14, v20 offset:1056
	ds_write_b32 v14, v21 offset:1060
	ds_write_b32 v14, v22 offset:1064
	ds_write_b32 v14, v23 offset:1068
	s_waitcnt vmcnt(5)
	ds_write_b32 v14, v24 offset:2112
	ds_write_b32 v14, v25 offset:2116
	ds_write_b32 v14, v26 offset:2120
	ds_write_b32 v14, v27 offset:2124
	s_waitcnt vmcnt(4)
	ds_write_b32 v14, v28 offset:3168
	ds_write_b32 v14, v29 offset:3172
	ds_write_b32 v14, v30 offset:3176
	ds_write_b32 v14, v31 offset:3180
	s_waitcnt vmcnt(3)
	ds_write_b32 v14, v32 offset:4224
	ds_write_b32 v14, v33 offset:4228
	ds_write_b32 v14, v34 offset:4232
	ds_write_b32 v14, v35 offset:4236
	s_waitcnt vmcnt(2)
	ds_write_b32 v14, v36 offset:5280
	ds_write_b32 v14, v37 offset:5284
	ds_write_b32 v14, v38 offset:5288
	ds_write_b32 v14, v39 offset:5292
	s_waitcnt vmcnt(1)
	ds_write_b32 v14, v40 offset:6336
	ds_write_b32 v14, v41 offset:6340
	ds_write_b32 v14, v42 offset:6344
	ds_write_b32 v14, v43 offset:6348
	s_waitcnt vmcnt(0)
	ds_write_b32 v14, v44 offset:7392
	ds_write_b32 v14, v45 offset:7396
	ds_write_b32 v14, v46 offset:7400
	ds_write_b32 v14, v47 offset:7404
	s_waitcnt lgkmcnt(0)
	ds_read2_b32 v[80:81], v15 offset0:0 offset1:33
	ds_read2_b32 v[82:83], v15 offset0:66 offset1:99
	ds_read2_b32 v[84:85], v15 offset0:132 offset1:165
	ds_read2_b32 v[86:87], v15 offset0:198 offset1:231
	ds_read2_b32 v[88:89], v15 offset0:8 offset1:41
	ds_read2_b32 v[90:91], v15 offset0:74 offset1:107
	ds_read2_b32 v[92:93], v15 offset0:140 offset1:173
	ds_read2_b32 v[94:95], v15 offset0:206 offset1:239
	s_waitcnt lgkmcnt(4)
	v_cvt_pk_bf16_f32 v112, v80, v81
	v_cvt_pk_bf16_f32 v113, v82, v83
	v_cvt_pk_bf16_f32 v114, v84, v85
	v_cvt_pk_bf16_f32 v115, v86, v87
	global_store_dwordx4 v4, v[112:115], s[16:17]
	s_waitcnt lgkmcnt(0)
	v_cvt_pk_bf16_f32 v116, v88, v89
	v_cvt_pk_bf16_f32 v117, v90, v91
	v_cvt_pk_bf16_f32 v118, v92, v93
	v_cvt_pk_bf16_f32 v119, v94, v95
	global_store_dwordx4 v5, v[116:119], s[16:17]
	ds_read2_b32 v[96:97], v15 offset0:16 offset1:49
	ds_read2_b32 v[98:99], v15 offset0:82 offset1:115
	ds_read2_b32 v[100:101], v15 offset0:148 offset1:181
	ds_read2_b32 v[102:103], v15 offset0:214 offset1:247
	ds_read2_b32 v[104:105], v15 offset0:24 offset1:57
	ds_read2_b32 v[106:107], v15 offset0:90 offset1:123
	ds_read2_b32 v[108:109], v15 offset0:156 offset1:189
	ds_read2_b32 v[110:111], v15 offset0:222 offset1:255
	s_waitcnt lgkmcnt(4)
	v_cvt_pk_bf16_f32 v120, v96, v97
	v_cvt_pk_bf16_f32 v121, v98, v99
	v_cvt_pk_bf16_f32 v122, v100, v101
	v_cvt_pk_bf16_f32 v123, v102, v103
	global_store_dwordx4 v6, v[120:123], s[16:17]
	s_waitcnt lgkmcnt(0)
	v_cvt_pk_bf16_f32 v124, v104, v105
	v_cvt_pk_bf16_f32 v125, v106, v107
	v_cvt_pk_bf16_f32 v126, v108, v109
	v_cvt_pk_bf16_f32 v127, v110, v111
	global_store_dwordx4 v7, v[124:127], s[16:17]
	s_addk_i32 s26, 0x300
	s_branch .Lffn2w_w4

;     __device__ __forceinline__ unsigned char* ws() const { return (unsigned char*)ptr(37); }
; #define ws (p.ws())
; __device__ __forceinline__ void phase_mixer(const Ctx& p, LAS unsigned char* lds) {
;     if (blockIdx.x < 128) scan_unit(p, blockIdx.x >> 2, blockIdx.x & 3, lds);
;     else { const int u0 = (blockIdx.x - 128) * 2; scan_unit(p, 32 + (u0 >> 2), u0 & 3, lds); scan_unit(p, 32 + ((u0 + 1) >> 2), (u0 + 1) & 3, lds); }
;     if (blockIdx.x < 128) return;
; __device__ __forceinline__ void sub_barrier(const Ctx& p, unsigned n) {
;     asm volatile("s_waitcnt vmcnt(0)" ::: "memory");
;     __syncthreads();
;     if (threadIdx.x == 0) {
;         unsigned* c = (unsigned*)(p.ws() + WS_CTR) + 128;
;         __builtin_amdgcn_fence(__ATOMIC_RELEASE, "agent");
;         asm volatile("s_waitcnt vmcnt(0)" ::: "memory");
;         __hip_atomic_fetch_add(c, 1u, __ATOMIC_RELAXED, __HIP_MEMORY_SCOPE_AGENT);
;         while (__hip_atomic_load(c, __ATOMIC_RELAXED, __HIP_MEMORY_SCOPE_AGENT) < n) __builtin_amdgcn_s_sleep(20);
;         __builtin_amdgcn_fence(__ATOMIC_ACQUIRE, "agent");
;         asm volatile("s_waitcnt vmcnt(0)" ::: "memory");
;     }
;     __syncthreads();
; }
.Lscan_ffn2w:
.Lffn2w_done:
	s_cmpk_gt_u32 s28, 3
	s_cbranch_scc1 .Ltg_scan_skip
	s_waitcnt vmcnt(0) lgkmcnt(0)
	s_barrier
	v_cmp_eq_u32_e32 vcc, 0, v180
	s_and_saveexec_b64 s[2:3], vcc
	s_cbranch_execz .Ltg_sync_done
	v_mov_b32_e32 v0, 0x23528
	ds_read_b64 v[0:1], v0
	s_waitcnt lgkmcnt(0)
	v_readfirstlane_b32 s4, v0
	v_readfirstlane_b32 s5, v1
	s_nop 4
	s_add_u32 s4, s4, 0x3180200
	s_addc_u32 s5, s5, 0
	v_mov_b32_e32 v0, 0
